# GLA scan: full LDS drains in front of the masked staging writes removed (five of six unrolled steps)
# speedup vs baseline: 1.0101x; 1.0037x over previous
; DI void gla_scan_item(const P& p, int seq, unsigned char* smem) {
;     ...
;     auto loadr = [&](GlaRegs& R, int c) {
;         if (c >= 72) return;
;         { const int pos = tid >> 4, ch = tid & 15; R.rv = *(const u32x4*)(S + (size_t)prow(b, dir, 32 * c + pos) * NP + C_GLA_V + 128 * h + 8 * ch); }
;         { const int t2 = tid & 255, pos = t2 >> 3, ch = t2 & 7; const bf16_t* src = (tid < 256 ? QT : KO) + ((size_t)seq * PT + 32 * c + pos) * 64 + 8 * ch; R.rq = __builtin_nontemporal_load((const u32x4*)src); }
;         if (tid < 128) { const int i = tid >> 2, ch = tid & 3; R.ra = __builtin_nontemporal_load((const u32x4*)(AT + (((size_t)seq * 72 + c) * 32 + i) * 32 + 8 * ch)); }
;     ...
;     auto compute = [&](int c) {
;         const unsigned char* base = smem + (c & 1) * BUFB;
;         const bf16_t* sat = (const bf16_t*)base; const bf16_t* sqt = (const bf16_t*)(base + 2560); const bf16_t* sko = (const bf16_t*)(base + 2560 + 4608); const bf16_t* sv = (const bf16_t*)(base + 2560 + 9216); const float* sdc = (const float*)(base + 2560 + 9216 + 8704);
;         const int dv0 = 16 * w;
;         const bf16x8 vb = tr2(sv + (8 * g + q4) * 136 + dv0 + 4 * p4, sv + (8 * g + 4 + q4) * 136 + dv0 + 4 * p4);
;         bf16x8 bs[2];
;         bs[0] = packacc(st[0], st[1]); bs[1] = packacc(st[2], st[3]);
; #pragma unroll
;         for (int mt = 0; mt < 2; ++mt) {
;             f32x4 acc = (f32x4){0.f, 0.f, 0.f, 0.f};
;             acc = mfma16(vb, ld8(sat + (16 * mt + l15) * 40 + 8 * g), acc);
; #pragma unroll
;             for (int ks = 0; ks < 2; ++ks) {
;                 const bf16_t* r0 = sqt + (16 * mt + l15) * 72 + 32 * ks + 4 * g;
;                 acc = mfma16(bs[ks], ld4x2(r0, r0 + 16), acc);
;             }
;             bf16_t* ob = OG + (size_t)prow(b, dir, 32 * c) * 512 + 128 * h;
;             u32x2 ov; ov.x = pk2(acc[0], acc[1]); ov.y = pk2(acc[2], acc[3]);
;             *(u32x2*)(ob + sgn * ((16 * mt + l15) * 512) + dv0 + 4 * g) = ov;
;         }
; #pragma unroll
;         for (int dt = 0; dt < 4; ++dt) {
;             const bf16x8 ak = tr2(sko + (8 * g + q4) * 72 + 16 * dt + 4 * p4, sko + (8 * g + 4 + q4) * 72 + 16 * dt + 4 * p4);
; #pragma unroll
;             for (int r = 0; r < 4; ++r) st[dt][r] *= sdc[16 * dt + 4 * g + r];
;             st[dt] = mfma16(ak, vb, st[dt]);
;         }
;     };
.LBB0_590:
	ds_read_b64_tr_b16 v[200:201], v123 offset:11776
	ds_read_b64_tr_b16 v[202:203], v124 offset:11776
	ds_read_b128 v[204:207], v125
	ds_read_b128 v[216:219], v127
	ds_read_b64_tr_b16 v[238:239], v144 offset:7168
	ds_read_b64_tr_b16 v[242:243], v144 offset:7200
	ds_read_b64_tr_b16 v[236:237], v143 offset:7168
	ds_read_b64_tr_b16 v[240:241], v143 offset:7200
	ds_read_b64_tr_b16 v[248:249], v143 offset:7232
	ds_read_b64_tr_b16 v[250:251], v144 offset:7232
	v_cvt_pk_bf16_f32 v96, v84, s0
	v_cvt_pk_bf16_f32 v99, v85, s0
	v_cvt_pk_bf16_f32 v151, v78, s0
	v_cvt_pk_bf16_f32 v152, v79, s0
	v_cvt_pk_bf16_f32 v97, v86, s0
	v_cvt_pk_bf16_f32 v134, v87, s0
	v_cvt_pk_bf16_f32 v98, v76, s0
	v_cvt_pk_bf16_f32 v135, v77, s0
	v_perm_b32 v96, v99, v96, s25
	v_perm_b32 v99, v152, v151, s25
	v_add_u32_e32 v152, 0x800, v126
	ds_read2_b64 v[208:211], v152 offset0:64 offset1:68
	ds_read2_b64 v[212:215], v152 offset0:72 offset1:76
	v_perm_b32 v98, v135, v98, s25
	v_perm_b32 v97, v134, v97, s25
	s_sub_i32 s4, s26, 64
	s_add_i32 s5, s26, 0xfffffec0
	s_add_i32 s6, s27, 0xa0
	s_add_i32 s7, s27, 0xfffff8a0
	s_waitcnt lgkmcnt(9)
	v_mfma_f32_16x16x32_bf16 v[92:95], v[200:203], v[204:207], 0
	s_and_b64 s[2:3], s[0:1], exec
	s_cselect_b32 s2, s4, s7
	v_cvt_pk_bf16_f32 v153, v80, s0
	v_cvt_pk_bf16_f32 v158, v81, s0
	v_cvt_pk_bf16_f32 v159, v82, s0
	v_cvt_pk_bf16_f32 v160, v83, s0
	v_cvt_pk_bf16_f32 v161, v72, s0
	v_cvt_pk_bf16_f32 v162, v73, s0
	v_cvt_pk_bf16_f32 v163, v74, s0
	v_cvt_pk_bf16_f32 v164, v75, s0
	s_add_i32 s4, s2, s22
	s_and_b64 s[2:3], s[0:1], exec
	s_waitcnt lgkmcnt(1)
	v_mfma_f32_16x16x32_bf16 v[92:95], v[96:99], v[208:211], v[92:95]
	ds_read_b64_tr_b16 v[208:209], v143 offset:7264
	ds_read_b64_tr_b16 v[210:211], v144 offset:7264
	v_perm_b32 v156, v162, v161, s25
	v_perm_b32 v155, v160, v159, s25
	v_perm_b32 v154, v158, v153, s25
	v_perm_b32 v157, v164, v163, s25
	s_cselect_b32 s2, s5, s6
	s_add_i32 s5, s2, s21
	s_cmp_lt_u32 s24, 8
	s_cselect_b64 s[36:37], -1, 0
	s_waitcnt lgkmcnt(2)
	v_mfma_f32_16x16x32_bf16 v[92:95], v[154:157], v[212:215], v[92:95]
	s_and_b64 s[2:3], s[36:37], exec
	s_cselect_b32 s2, s4, s5
	s_ashr_i32 s3, s2, 31
	s_lshl_b64 s[42:43], s[2:3], 10
	v_add_u32_e32 v151, 0x800, v142
	ds_read2_b64 v[224:227], v151 offset0:64 offset1:68
	ds_read2_b64 v[228:231], v151 offset0:72 offset1:76
	s_nop 2
	v_cvt_pk_bf16_f32 v92, v92, v93
	v_cvt_pk_bf16_f32 v93, v94, v95
	v_lshl_add_u64 v[94:95], v[100:101], 0, s[42:43]
	global_store_dwordx2 v[94:95], v[92:93], off
	v_mfma_f32_16x16x32_bf16 v[92:95], v[200:203], v[216:219], 0
	v_add_u32_e32 v153, 0x5000, v145
	ds_read2_b32 v[232:233], v153 offset1:1
	s_waitcnt lgkmcnt(2)
	v_mfma_f32_16x16x32_bf16 v[92:95], v[96:99], v[224:227], v[92:95]
	v_add_u32_e32 v158, 0x5040, v145
	ds_read2_b32 v[244:245], v158 offset1:1
	v_add_u32_e32 v161, 0x50c0, v145
	ds_read2_b32 v[212:213], v161 offset1:1
	s_waitcnt lgkmcnt(3)
	v_mfma_f32_16x16x32_bf16 v[92:95], v[154:157], v[228:231], v[92:95]
	v_add_u32_e32 v156, 0x5008, v145
	ds_read2_b32 v[234:235], v156 offset1:1
	v_add_u32_e32 v157, 0x5048, v145
	ds_read2_b32 v[246:247], v157 offset1:1
	v_add_u32_e32 v154, 0x5080, v145
	ds_read2_b32 v[204:205], v154 offset1:1
	s_nop 4
	v_cvt_pk_bf16_f32 v92, v92, v93
	v_cvt_pk_bf16_f32 v93, v94, v95
	v_lshl_add_u64 v[94:95], v[102:103], 0, s[42:43]
	global_store_dwordx2 v[94:95], v[92:93], off
	v_add_u32_e32 v155, 0x5088, v145
	ds_read2_b32 v[206:207], v155 offset1:1
	v_add_u32_e32 v160, 0x50c8, v145
	ds_read2_b32 v[214:215], v160 offset1:1
	s_waitcnt lgkmcnt(7)
	v_pk_mul_f32 v[84:85], v[84:85], v[232:233]
	s_waitcnt lgkmcnt(4)
	v_pk_mul_f32 v[86:87], v[86:87], v[234:235]
	s_nop 1
	v_mfma_f32_16x16x32_bf16 v[84:87], v[236:239], v[200:203], v[84:87]
	v_pk_mul_f32 v[76:77], v[76:77], v[244:245]
	s_waitcnt lgkmcnt(3)
	v_pk_mul_f32 v[78:79], v[78:79], v[246:247]
	s_nop 1
	v_mfma_f32_16x16x32_bf16 v[76:79], v[240:243], v[200:203], v[76:79]
	s_waitcnt lgkmcnt(2)
	v_pk_mul_f32 v[80:81], v[80:81], v[204:205]
	s_waitcnt lgkmcnt(1)
	v_pk_mul_f32 v[82:83], v[82:83], v[206:207]
	s_nop 1
	v_mfma_f32_16x16x32_bf16 v[80:83], v[248:251], v[200:203], v[80:83]
	s_waitcnt vmcnt(11)
	ds_write_b128 v121, v[12:15] offset:32512
	s_waitcnt vmcnt(10)
	ds_write_b128 v122, v[20:23] offset:20736
	v_pk_mul_f32 v[72:73], v[72:73], v[212:213]
	s_waitcnt lgkmcnt(2)
	v_pk_mul_f32 v[74:75], v[74:75], v[214:215]
	s_nop 1
	v_mfma_f32_16x16x32_bf16 v[72:75], v[208:211], v[200:203], v[72:75]
	s_and_saveexec_b64 s[42:43], s[38:39]
	ds_write_b128 v148, v[16:19] offset:20736
	s_or_b64 exec, exec, s[42:43]
	s_and_saveexec_b64 s[42:43], s[40:41]
	ds_write_b32 v149, v116 offset:40704
	s_or_b64 exec, exec, s[42:43]
	s_cmp_gt_u32 s24, 64
	s_waitcnt lgkmcnt(0)
	s_barrier
	s_cbranch_scc1 .LBB0_600
	v_add_u32_e32 v12, 0xa0, v150
	s_movk_i32 s2, 0x100
	v_cmp_gt_i32_e32 vcc, s2, v12
	v_add_u32_e32 v13, 0xffffffa0, v150
	v_mov_b32_e32 v15, s22
	v_cndmask_b32_e32 v14, v174, v175, vcc
	v_add3_u32 v14, v132, v14, s27
	v_cndmask_b32_e32 v12, v13, v12, vcc
	v_mov_b32_e32 v13, s21
	v_add_u32_e32 v14, 0xfffff6c1, v14
	v_cndmask_b32_e32 v13, v13, v15, vcc
	v_cndmask_b32_e64 v12, v14, v12, s[0:1]
	v_add_u32_e32 v12, v12, v13
	s_movk_i32 s2, 0x3800
	v_add_co_u32_e32 v20, vcc, 0x7000, v112
	v_mad_i64_i32 v[12:13], s[2:3], v12, s2, v[104:105]
	s_nop 0
	v_addc_co_u32_e32 v21, vcc, 0, v113, vcc
	global_load_dwordx4 v[12:15], v[12:13], off offset:1024
	s_nop 0
	global_load_dwordx4 v[20:23], v[20:21], off nt
	s_and_saveexec_b64 s[42:43], s[38:39]
	s_cbranch_execz .LBB0_597
	v_lshl_add_u64 v[16:17], v[106:107], 0, s[44:45]
	v_add_co_u32_e32 v16, vcc, 0x1283f000, v16
	s_nop 1
	v_addc_co_u32_e32 v17, vcc, 0, v17, vcc
	global_load_dwordx4 v[16:19], v[16:17], off offset:2048 nt

; DI void gla_scan_item(const P& p, int seq, unsigned char* smem) {
;     ...
;     auto loadr = [&](GlaRegs& R, int c) {
;         if (c >= 72) return;
;         { const int pos = tid >> 4, ch = tid & 15; R.rv = *(const u32x4*)(S + (size_t)prow(b, dir, 32 * c + pos) * NP + C_GLA_V + 128 * h + 8 * ch); }
;         { const int t2 = tid & 255, pos = t2 >> 3, ch = t2 & 7; const bf16_t* src = (tid < 256 ? QT : KO) + ((size_t)seq * PT + 32 * c + pos) * 64 + 8 * ch; R.rq = __builtin_nontemporal_load((const u32x4*)src); }
;         if (tid < 128) { const int i = tid >> 2, ch = tid & 3; R.ra = __builtin_nontemporal_load((const u32x4*)(AT + (((size_t)seq * 72 + c) * 32 + i) * 32 + 8 * ch)); }
;     ...
;     auto compute = [&](int c) {
;         const unsigned char* base = smem + (c & 1) * BUFB;
;         const bf16_t* sat = (const bf16_t*)base; const bf16_t* sqt = (const bf16_t*)(base + 2560); const bf16_t* sko = (const bf16_t*)(base + 2560 + 4608); const bf16_t* sv = (const bf16_t*)(base + 2560 + 9216); const float* sdc = (const float*)(base + 2560 + 9216 + 8704);
;         const int dv0 = 16 * w;
;         const bf16x8 vb = tr2(sv + (8 * g + q4) * 136 + dv0 + 4 * p4, sv + (8 * g + 4 + q4) * 136 + dv0 + 4 * p4);
;         bf16x8 bs[2];
;         bs[0] = packacc(st[0], st[1]); bs[1] = packacc(st[2], st[3]);
; #pragma unroll
;         for (int mt = 0; mt < 2; ++mt) {
;             f32x4 acc = (f32x4){0.f, 0.f, 0.f, 0.f};
;             acc = mfma16(vb, ld8(sat + (16 * mt + l15) * 40 + 8 * g), acc);
; #pragma unroll
;             for (int ks = 0; ks < 2; ++ks) {
;                 const bf16_t* r0 = sqt + (16 * mt + l15) * 72 + 32 * ks + 4 * g;
;                 acc = mfma16(bs[ks], ld4x2(r0, r0 + 16), acc);
;             }
;             bf16_t* ob = OG + (size_t)prow(b, dir, 32 * c) * 512 + 128 * h;
;             u32x2 ov; ov.x = pk2(acc[0], acc[1]); ov.y = pk2(acc[2], acc[3]);
;             *(u32x2*)(ob + sgn * ((16 * mt + l15) * 512) + dv0 + 4 * g) = ov;
;         }
; #pragma unroll
;         for (int dt = 0; dt < 4; ++dt) {
;             const bf16x8 ak = tr2(sko + (8 * g + q4) * 72 + 16 * dt + 4 * p4, sko + (8 * g + 4 + q4) * 72 + 16 * dt + 4 * p4);
; #pragma unroll
;             for (int r = 0; r < 4; ++r) st[dt][r] *= sdc[16 * dt + 4 * g + r];
;             st[dt] = mfma16(ak, vb, st[dt]);
;         }
;     };
.LBB0_600:
	ds_read_b64_tr_b16 v[200:201], v123 offset:32512
	ds_read_b64_tr_b16 v[202:203], v124 offset:32512
	ds_read_b128 v[204:207], v125 offset:20736
	ds_read_b128 v[216:219], v127 offset:20736
	ds_read_b64_tr_b16 v[238:239], v147 offset:27904
	ds_read_b64_tr_b16 v[242:243], v147 offset:27936
	ds_read_b64_tr_b16 v[236:237], v146 offset:27904
	ds_read_b64_tr_b16 v[240:241], v146 offset:27936
	ds_read_b64_tr_b16 v[248:249], v146 offset:27968
	ds_read_b64_tr_b16 v[250:251], v147 offset:27968
	v_cvt_pk_bf16_f32 v96, v84, s0
	v_cvt_pk_bf16_f32 v99, v85, s0
	v_cvt_pk_bf16_f32 v159, v78, s0
	v_cvt_pk_bf16_f32 v162, v79, s0
	v_cvt_pk_bf16_f32 v97, v86, s0
	v_cvt_pk_bf16_f32 v134, v87, s0
	v_cvt_pk_bf16_f32 v98, v76, s0
	v_cvt_pk_bf16_f32 v135, v77, s0
	v_perm_b32 v96, v99, v96, s25
	v_perm_b32 v99, v162, v159, s25
	v_add_u32_e32 v159, 0x5800, v126
	ds_read2_b64 v[208:211], v159 offset0:96 offset1:100
	ds_read2_b64 v[212:215], v159 offset0:104 offset1:108
	v_perm_b32 v98, v135, v98, s25
	v_perm_b32 v97, v134, v97, s25
	s_waitcnt lgkmcnt(9)
	v_mfma_f32_16x16x32_bf16 v[88:91], v[200:203], v[204:207], 0
	s_sub_i32 s4, s26, 32
	s_add_i32 s5, s26, 0xfffffee0
	s_add_i32 s6, s27, 0x80
	s_add_i32 s7, s27, 0xfffff880
	v_cvt_pk_bf16_f32 v183, v80, s0
	v_cvt_pk_bf16_f32 v184, v81, s0
	v_cvt_pk_bf16_f32 v185, v82, s0
	v_cvt_pk_bf16_f32 v186, v83, s0
	v_cvt_pk_bf16_f32 v187, v72, s0
	v_cvt_pk_bf16_f32 v188, v73, s0
	v_cvt_pk_bf16_f32 v189, v74, s0
	v_cvt_pk_bf16_f32 v190, v75, s0
	s_and_b64 s[2:3], s[0:1], exec
	s_waitcnt lgkmcnt(1)
	v_mfma_f32_16x16x32_bf16 v[162:165], v[96:99], v[208:211], v[88:91]
	ds_read_b64_tr_b16 v[208:209], v146 offset:28000
	ds_read_b64_tr_b16 v[210:211], v147 offset:28000
	s_cselect_b32 s2, s4, s7
	s_add_i32 s4, s2, s22
	s_and_b64 s[2:3], s[0:1], exec
	v_perm_b32 v90, v188, v187, s25
	v_perm_b32 v89, v186, v185, s25
	v_perm_b32 v88, v184, v183, s25
	v_perm_b32 v91, v190, v189, s25
	s_cselect_b32 s2, s5, s6
	s_add_i32 s5, s2, s21
	s_waitcnt lgkmcnt(2)
	v_mfma_f32_16x16x32_bf16 v[162:165], v[88:91], v[212:215], v[162:165]
	s_and_b64 s[2:3], s[36:37], exec
	s_cselect_b32 s2, s4, s5
	s_ashr_i32 s3, s2, 31
	s_lshl_b64 s[36:37], s[2:3], 10
	s_nop 3
	v_cvt_pk_bf16_f32 v134, v162, v163
	v_cvt_pk_bf16_f32 v135, v164, v165
	v_lshl_add_u64 v[162:163], v[100:101], 0, s[36:37]
	global_store_dwordx2 v[162:163], v[134:135], off
	v_mfma_f32_16x16x32_bf16 v[184:187], v[200:203], v[216:219], 0
	v_add_u32_e32 v162, 0x5800, v142
	ds_read2_b64 v[224:227], v162 offset0:96 offset1:100
	ds_read2_b64 v[228:231], v162 offset0:104 offset1:108
	v_add_u32_e32 v163, 0xa100, v145
	ds_read2_b32 v[232:233], v163 offset1:1
	s_waitcnt lgkmcnt(2)
	v_mfma_f32_16x16x32_bf16 v[96:99], v[96:99], v[224:227], v[184:187]
	s_nop 2
	v_add_u32_e32 v183, 0xa108, v145
	ds_read2_b32 v[234:235], v183 offset1:1
	v_add_u32_e32 v164, 0xa180, v145
	ds_read2_b32 v[204:205], v164 offset1:1
	s_waitcnt lgkmcnt(3)
	v_mfma_f32_16x16x32_bf16 v[88:91], v[88:91], v[228:231], v[96:99]
	v_add_u32_e32 v185, 0xa140, v145
	ds_read2_b32 v[244:245], v185 offset1:1
	v_add_u32_e32 v184, 0xa148, v145
	ds_read2_b32 v[246:247], v184 offset1:1
	v_add_u32_e32 v165, 0xa188, v145
	ds_read2_b32 v[206:207], v165 offset1:1
	s_nop 4
	v_cvt_pk_bf16_f32 v88, v88, v89
	v_cvt_pk_bf16_f32 v89, v90, v91
	v_lshl_add_u64 v[90:91], v[102:103], 0, s[36:37]
	global_store_dwordx2 v[90:91], v[88:89], off
	v_add_u32_e32 v187, 0xa1c0, v145
	ds_read2_b32 v[212:213], v187 offset1:1
	v_add_u32_e32 v186, 0xa1c8, v145
	ds_read2_b32 v[214:215], v186 offset1:1
	s_waitcnt lgkmcnt(7)
	v_pk_mul_f32 v[84:85], v[84:85], v[232:233]
	s_waitcnt lgkmcnt(6)
	v_pk_mul_f32 v[86:87], v[86:87], v[234:235]
	s_nop 1
	v_mfma_f32_16x16x32_bf16 v[88:91], v[236:239], v[200:203], v[84:87]
	s_nop 2
	s_waitcnt lgkmcnt(4)
	v_pk_mul_f32 v[76:77], v[76:77], v[244:245]
	s_waitcnt lgkmcnt(3)
	v_pk_mul_f32 v[78:79], v[78:79], v[246:247]
	s_nop 1
	v_mfma_f32_16x16x32_bf16 v[84:87], v[240:243], v[200:203], v[76:79]
	s_nop 2
	v_pk_mul_f32 v[80:81], v[80:81], v[204:205]
	s_waitcnt lgkmcnt(2)
	v_pk_mul_f32 v[82:83], v[82:83], v[206:207]
	s_nop 1
	v_mfma_f32_16x16x32_bf16 v[76:79], v[248:251], v[200:203], v[80:83]
	s_nop 2
	s_waitcnt vmcnt(11)
	ds_write_b128 v121, v[24:27] offset:11776
	s_waitcnt vmcnt(10)
	ds_write_b128 v122, v[32:35]
	s_waitcnt lgkmcnt(3)
	v_pk_mul_f32 v[72:73], v[72:73], v[212:213]
	s_waitcnt lgkmcnt(2)
	v_pk_mul_f32 v[74:75], v[74:75], v[214:215]
	s_nop 1
	v_mfma_f32_16x16x32_bf16 v[80:83], v[208:211], v[200:203], v[72:75]
	s_and_saveexec_b64 s[36:37], s[38:39]
	ds_write_b128 v148, v[28:31]
	s_or_b64 exec, exec, s[36:37]
	s_and_saveexec_b64 s[36:37], s[40:41]
	ds_write_b32 v149, v117 offset:19968
	s_or_b64 exec, exec, s[36:37]
	s_cmp_gt_u32 s24, 63
	s_waitcnt lgkmcnt(0)
	s_barrier
	s_cbranch_scc1 .LBB0_610
	v_add_u32_e32 v24, 0xc0, v150
	s_movk_i32 s2, 0x100
	v_cmp_gt_i32_e32 vcc, s2, v24
	v_subrev_u32_e32 v25, 64, v150
	v_mov_b32_e32 v27, s22
	v_cndmask_b32_e32 v26, v174, v175, vcc
	v_add3_u32 v26, v132, v26, s27
	v_cndmask_b32_e32 v24, v25, v24, vcc
	v_mov_b32_e32 v25, s21
	v_add_u32_e32 v26, 0xfffff6a1, v26
	v_cndmask_b32_e32 v25, v25, v27, vcc
	v_cndmask_b32_e64 v24, v26, v24, s[0:1]
	v_add_u32_e32 v24, v24, v25
	s_movk_i32 s2, 0x3800
	v_add_co_u32_e32 v32, vcc, 0x8000, v112
	v_mad_i64_i32 v[24:25], s[2:3], v24, s2, v[104:105]
	s_nop 0
	v_addc_co_u32_e32 v33, vcc, 0, v113, vcc
	global_load_dwordx4 v[24:27], v[24:25], off offset:1024
	s_nop 0
	global_load_dwordx4 v[32:35], v[32:33], off nt
	s_and_saveexec_b64 s[36:37], s[38:39]
	s_cbranch_execz .LBB0_607
	v_lshl_add_u64 v[28:29], v[106:107], 0, s[44:45]
	v_add_co_u32_e32 v28, vcc, 0x12840000, v28
	s_nop 1
	v_addc_co_u32_e32 v29, vcc, 0, v29, vcc
	global_load_dwordx4 v[28:31], v[28:29], off nt

; DI void gla_scan_item(const P& p, int seq, unsigned char* smem) {
;     ...
;     auto loadr = [&](GlaRegs& R, int c) {
;         if (c >= 72) return;
;         { const int pos = tid >> 4, ch = tid & 15; R.rv = *(const u32x4*)(S + (size_t)prow(b, dir, 32 * c + pos) * NP + C_GLA_V + 128 * h + 8 * ch); }
;         { const int t2 = tid & 255, pos = t2 >> 3, ch = t2 & 7; const bf16_t* src = (tid < 256 ? QT : KO) + ((size_t)seq * PT + 32 * c + pos) * 64 + 8 * ch; R.rq = __builtin_nontemporal_load((const u32x4*)src); }
;         if (tid < 128) { const int i = tid >> 2, ch = tid & 3; R.ra = __builtin_nontemporal_load((const u32x4*)(AT + (((size_t)seq * 72 + c) * 32 + i) * 32 + 8 * ch)); }
;     ...
;     auto compute = [&](int c) {
;         const unsigned char* base = smem + (c & 1) * BUFB;
;         const bf16_t* sat = (const bf16_t*)base; const bf16_t* sqt = (const bf16_t*)(base + 2560); const bf16_t* sko = (const bf16_t*)(base + 2560 + 4608); const bf16_t* sv = (const bf16_t*)(base + 2560 + 9216); const float* sdc = (const float*)(base + 2560 + 9216 + 8704);
;         const int dv0 = 16 * w;
;         const bf16x8 vb = tr2(sv + (8 * g + q4) * 136 + dv0 + 4 * p4, sv + (8 * g + 4 + q4) * 136 + dv0 + 4 * p4);
;         bf16x8 bs[2];
;         bs[0] = packacc(st[0], st[1]); bs[1] = packacc(st[2], st[3]);
; #pragma unroll
;         for (int mt = 0; mt < 2; ++mt) {
;             f32x4 acc = (f32x4){0.f, 0.f, 0.f, 0.f};
;             acc = mfma16(vb, ld8(sat + (16 * mt + l15) * 40 + 8 * g), acc);
; #pragma unroll
;             for (int ks = 0; ks < 2; ++ks) {
;                 const bf16_t* r0 = sqt + (16 * mt + l15) * 72 + 32 * ks + 4 * g;
;                 acc = mfma16(bs[ks], ld4x2(r0, r0 + 16), acc);
;             }
;             bf16_t* ob = OG + (size_t)prow(b, dir, 32 * c) * 512 + 128 * h;
;             u32x2 ov; ov.x = pk2(acc[0], acc[1]); ov.y = pk2(acc[2], acc[3]);
;             *(u32x2*)(ob + sgn * ((16 * mt + l15) * 512) + dv0 + 4 * g) = ov;
;         }
; #pragma unroll
;         for (int dt = 0; dt < 4; ++dt) {
;             const bf16x8 ak = tr2(sko + (8 * g + q4) * 72 + 16 * dt + 4 * p4, sko + (8 * g + 4 + q4) * 72 + 16 * dt + 4 * p4);
; #pragma unroll
;             for (int r = 0; r < 4; ++r) st[dt][r] *= sdc[16 * dt + 4 * g + r];
;             st[dt] = mfma16(ak, vb, st[dt]);
;         }
;     };
.LBB0_610:
	ds_read_b64_tr_b16 v[200:201], v123 offset:11776
	ds_read_b64_tr_b16 v[202:203], v124 offset:11776
	ds_read_b128 v[204:207], v125
	ds_read2_b64 v[208:211], v152 offset0:64 offset1:68
	ds_read2_b64 v[212:215], v152 offset0:72 offset1:76
	ds_read2_b64 v[216:219], v151 offset0:64 offset1:68
	ds_read_b128 v[224:227], v127
	ds_read2_b64 v[228:231], v151 offset0:72 offset1:76
	ds_read2_b32 v[232:233], v153 offset1:1
	ds_read2_b32 v[234:235], v156 offset1:1
	ds_read_b64_tr_b16 v[238:239], v144 offset:7168
	ds_read_b64_tr_b16 v[242:243], v144 offset:7200
	v_cvt_pk_bf16_f32 v96, v88, s0
	v_cvt_pk_bf16_f32 v99, v89, s0
	v_cvt_pk_bf16_f32 v97, v90, s0
	v_cvt_pk_bf16_f32 v134, v91, s0
	v_cvt_pk_bf16_f32 v98, v84, s0
	v_cvt_pk_bf16_f32 v135, v85, s0
	v_cvt_pk_bf16_f32 v188, v86, s0
	v_cvt_pk_bf16_f32 v189, v87, s0
	v_perm_b32 v98, v135, v98, s25
	v_perm_b32 v97, v134, v97, s25
	v_perm_b32 v96, v99, v96, s25
	v_perm_b32 v99, v189, v188, s25
	s_waitcnt lgkmcnt(9)
	v_mfma_f32_16x16x32_bf16 v[72:75], v[200:203], v[204:207], 0
	ds_read_b64_tr_b16 v[236:237], v143 offset:7168
	ds_read_b64_tr_b16 v[240:241], v143 offset:7200
	ds_read2_b32 v[244:245], v158 offset1:1
	s_add_i32 s4, s26, 0xffffff00
	s_add_i32 s5, s27, 0x60
	s_add_i32 s6, s27, 0xfffff860
	v_cvt_pk_bf16_f32 v192, v76, s0
	v_cvt_pk_bf16_f32 v193, v77, s0
	v_cvt_pk_bf16_f32 v194, v78, s0
	v_cvt_pk_bf16_f32 v195, v79, s0
	v_cvt_pk_bf16_f32 v196, v80, s0
	v_cvt_pk_bf16_f32 v197, v81, s0
	v_cvt_pk_bf16_f32 v198, v82, s0
	v_cvt_pk_bf16_f32 v199, v83, s0
	s_and_b64 s[2:3], s[0:1], exec
	s_cselect_b32 s2, s26, s6
	s_waitcnt lgkmcnt(11)
	v_mfma_f32_16x16x32_bf16 v[72:75], v[96:99], v[208:211], v[72:75]
	ds_read2_b32 v[246:247], v157 offset1:1
	v_perm_b32 v190, v197, v196, s25
	v_perm_b32 v189, v195, v194, s25
	v_perm_b32 v188, v193, v192, s25
	v_perm_b32 v191, v199, v198, s25
	s_add_i32 s6, s2, s22
	s_and_b64 s[2:3], s[0:1], exec
	s_cselect_b32 s2, s4, s5
	s_add_i32 s2, s2, s21
	s_cmp_lt_u32 s24, 6
	s_waitcnt lgkmcnt(11)
	v_mfma_f32_16x16x32_bf16 v[72:75], v[188:191], v[212:215], v[72:75]
	ds_read_b64_tr_b16 v[248:249], v143 offset:7232
	s_cselect_b32 s2, s6, s2
	s_ashr_i32 s3, s2, 31
	s_lshl_b64 s[36:37], s[2:3], 10
	s_nop 3
	v_cvt_pk_bf16_f32 v72, v72, v73
	v_cvt_pk_bf16_f32 v73, v74, v75
	v_lshl_add_u64 v[74:75], v[100:101], 0, s[36:37]
	global_store_dwordx2 v[74:75], v[72:73], off
	s_waitcnt lgkmcnt(10)
	v_mfma_f32_16x16x32_bf16 v[72:75], v[200:203], v[224:227], 0
	ds_read_b64_tr_b16 v[250:251], v144 offset:7232
	ds_read2_b32 v[204:205], v154 offset1:1
	v_mfma_f32_16x16x32_bf16 v[72:75], v[96:99], v[216:219], v[72:75]
	s_waitcnt lgkmcnt(11)
	v_mfma_f32_16x16x32_bf16 v[72:75], v[188:191], v[228:231], v[72:75]
	ds_read2_b32 v[206:207], v155 offset1:1
	s_nop 7
	v_cvt_pk_bf16_f32 v72, v72, v73
	v_cvt_pk_bf16_f32 v73, v74, v75
	v_lshl_add_u64 v[74:75], v[102:103], 0, s[36:37]
	global_store_dwordx2 v[74:75], v[72:73], off
	s_waitcnt lgkmcnt(11)
	v_pk_mul_f32 v[72:73], v[88:89], v[232:233]
	ds_read_b64_tr_b16 v[208:209], v143 offset:7264
	s_waitcnt lgkmcnt(11)
	v_pk_mul_f32 v[74:75], v[90:91], v[234:235]
	ds_read_b64_tr_b16 v[210:211], v144 offset:7264
	s_waitcnt lgkmcnt(9)
	v_mfma_f32_16x16x32_bf16 v[88:91], v[236:239], v[200:203], v[72:75]
	ds_read2_b32 v[212:213], v161 offset1:1
	ds_read2_b32 v[214:215], v160 offset1:1
	s_nop 2
	s_waitcnt lgkmcnt(9)
	v_pk_mul_f32 v[72:73], v[84:85], v[244:245]
	s_waitcnt lgkmcnt(8)
	v_pk_mul_f32 v[74:75], v[86:87], v[246:247]
	s_nop 1
	v_mfma_f32_16x16x32_bf16 v[72:75], v[240:243], v[200:203], v[72:75]
	s_waitcnt lgkmcnt(5)
	v_pk_mul_f32 v[76:77], v[76:77], v[204:205]
	s_waitcnt lgkmcnt(4)
	v_pk_mul_f32 v[78:79], v[78:79], v[206:207]
	s_nop 1
	v_mfma_f32_16x16x32_bf16 v[76:79], v[248:251], v[200:203], v[76:79]
	s_waitcnt vmcnt(11)
	ds_write_b128 v121, v[36:39] offset:32512
	s_waitcnt vmcnt(10)
	ds_write_b128 v122, v[44:47] offset:20736
	s_waitcnt lgkmcnt(3)
	v_pk_mul_f32 v[80:81], v[80:81], v[212:213]
	s_waitcnt lgkmcnt(2)
	v_pk_mul_f32 v[82:83], v[82:83], v[214:215]
	s_nop 1
	v_mfma_f32_16x16x32_bf16 v[80:83], v[208:211], v[200:203], v[80:83]
	s_and_saveexec_b64 s[36:37], s[38:39]
	ds_write_b128 v148, v[40:43] offset:20736
	s_or_b64 exec, exec, s[36:37]
	s_and_saveexec_b64 s[36:37], s[40:41]
	ds_write_b32 v149, v118 offset:40704
	s_or_b64 exec, exec, s[36:37]
	s_cmp_gt_u32 s24, 62
	s_waitcnt lgkmcnt(0)
	s_barrier
	s_cbranch_scc1 .LBB0_620
	v_add_u32_e32 v36, 0xe0, v150
	s_movk_i32 s2, 0x100
	v_cmp_gt_i32_e32 vcc, s2, v36
	v_subrev_u32_e32 v37, 32, v150
	v_mov_b32_e32 v39, s22
	v_cndmask_b32_e32 v38, v174, v175, vcc
	v_add3_u32 v38, v132, v38, s27
	v_cndmask_b32_e32 v36, v37, v36, vcc
	v_mov_b32_e32 v37, s21
	v_add_u32_e32 v38, 0xfffff681, v38
	v_cndmask_b32_e32 v37, v37, v39, vcc
	v_cndmask_b32_e64 v36, v38, v36, s[0:1]
	v_add_u32_e32 v36, v36, v37
	s_movk_i32 s2, 0x3800
	v_add_co_u32_e32 v44, vcc, 0x9000, v112
	v_mad_i64_i32 v[36:37], s[2:3], v36, s2, v[104:105]
	s_nop 0
	v_addc_co_u32_e32 v45, vcc, 0, v113, vcc
	global_load_dwordx4 v[36:39], v[36:37], off offset:1024
	s_nop 0
	global_load_dwordx4 v[44:47], v[44:45], off nt
	s_and_saveexec_b64 s[36:37], s[38:39]
	s_cbranch_execz .LBB0_617
	v_lshl_add_u64 v[40:41], v[106:107], 0, s[44:45]
	v_add_co_u32_e32 v40, vcc, 0x12840000, v40
	s_nop 1
	v_addc_co_u32_e32 v41, vcc, 0, v41, vcc
	global_load_dwordx4 v[40:43], v[40:41], off offset:2048 nt

; DI void gla_scan_item(const P& p, int seq, unsigned char* smem) {
;     ...
;     auto loadr = [&](GlaRegs& R, int c) {
;         if (c >= 72) return;
;         { const int pos = tid >> 4, ch = tid & 15; R.rv = *(const u32x4*)(S + (size_t)prow(b, dir, 32 * c + pos) * NP + C_GLA_V + 128 * h + 8 * ch); }
;         { const int t2 = tid & 255, pos = t2 >> 3, ch = t2 & 7; const bf16_t* src = (tid < 256 ? QT : KO) + ((size_t)seq * PT + 32 * c + pos) * 64 + 8 * ch; R.rq = __builtin_nontemporal_load((const u32x4*)src); }
;         if (tid < 128) { const int i = tid >> 2, ch = tid & 3; R.ra = __builtin_nontemporal_load((const u32x4*)(AT + (((size_t)seq * 72 + c) * 32 + i) * 32 + 8 * ch)); }
;     ...
;     auto compute = [&](int c) {
;         const unsigned char* base = smem + (c & 1) * BUFB;
;         const bf16_t* sat = (const bf16_t*)base; const bf16_t* sqt = (const bf16_t*)(base + 2560); const bf16_t* sko = (const bf16_t*)(base + 2560 + 4608); const bf16_t* sv = (const bf16_t*)(base + 2560 + 9216); const float* sdc = (const float*)(base + 2560 + 9216 + 8704);
;         const int dv0 = 16 * w;
;         const bf16x8 vb = tr2(sv + (8 * g + q4) * 136 + dv0 + 4 * p4, sv + (8 * g + 4 + q4) * 136 + dv0 + 4 * p4);
;         bf16x8 bs[2];
;         bs[0] = packacc(st[0], st[1]); bs[1] = packacc(st[2], st[3]);
; #pragma unroll
;         for (int mt = 0; mt < 2; ++mt) {
;             f32x4 acc = (f32x4){0.f, 0.f, 0.f, 0.f};
;             acc = mfma16(vb, ld8(sat + (16 * mt + l15) * 40 + 8 * g), acc);
; #pragma unroll
;             for (int ks = 0; ks < 2; ++ks) {
;                 const bf16_t* r0 = sqt + (16 * mt + l15) * 72 + 32 * ks + 4 * g;
;                 acc = mfma16(bs[ks], ld4x2(r0, r0 + 16), acc);
;             }
;             bf16_t* ob = OG + (size_t)prow(b, dir, 32 * c) * 512 + 128 * h;
;             u32x2 ov; ov.x = pk2(acc[0], acc[1]); ov.y = pk2(acc[2], acc[3]);
;             *(u32x2*)(ob + sgn * ((16 * mt + l15) * 512) + dv0 + 4 * g) = ov;
;         }
; #pragma unroll
;         for (int dt = 0; dt < 4; ++dt) {
;             const bf16x8 ak = tr2(sko + (8 * g + q4) * 72 + 16 * dt + 4 * p4, sko + (8 * g + 4 + q4) * 72 + 16 * dt + 4 * p4);
; #pragma unroll
;             for (int r = 0; r < 4; ++r) st[dt][r] *= sdc[16 * dt + 4 * g + r];
;             st[dt] = mfma16(ak, vb, st[dt]);
;         }
;     };
.LBB0_620:
	ds_read_b64_tr_b16 v[200:201], v123 offset:32512
	ds_read_b64_tr_b16 v[202:203], v124 offset:32512
	ds_read_b128 v[204:207], v125 offset:20736
	ds_read2_b64 v[208:211], v159 offset0:96 offset1:100
	ds_read2_b64 v[212:215], v159 offset0:104 offset1:108
	ds_read2_b64 v[216:219], v162 offset0:96 offset1:100
	ds_read_b128 v[224:227], v127 offset:20736
	ds_read2_b64 v[228:231], v162 offset0:104 offset1:108
	ds_read2_b32 v[232:233], v163 offset1:1
	ds_read2_b32 v[234:235], v183 offset1:1
	ds_read_b64_tr_b16 v[238:239], v147 offset:27904
	ds_read_b64_tr_b16 v[242:243], v147 offset:27936
	v_cvt_pk_bf16_f32 v96, v88, s0
	v_cvt_pk_bf16_f32 v99, v89, s0
	v_cvt_pk_bf16_f32 v97, v90, s0
	v_cvt_pk_bf16_f32 v134, v91, s0
	v_cvt_pk_bf16_f32 v98, v72, s0
	v_cvt_pk_bf16_f32 v135, v73, s0
	v_cvt_pk_bf16_f32 v188, v74, s0
	v_cvt_pk_bf16_f32 v189, v75, s0
	v_perm_b32 v98, v135, v98, s25
	v_perm_b32 v97, v134, v97, s25
	v_perm_b32 v96, v99, v96, s25
	v_perm_b32 v99, v189, v188, s25
	s_waitcnt lgkmcnt(9)
	v_mfma_f32_16x16x32_bf16 v[92:95], v[200:203], v[204:207], 0
	ds_read_b64_tr_b16 v[236:237], v146 offset:27904
	ds_read_b64_tr_b16 v[240:241], v146 offset:27936
	ds_read2_b32 v[244:245], v185 offset1:1
	s_add_i32 s4, s26, 32
	s_add_i32 s5, s26, 0xffffff20
	s_add_i32 s6, s27, 64
	s_add_i32 s7, s27, 0xfffff840
	v_cvt_pk_bf16_f32 v192, v76, s0
	v_cvt_pk_bf16_f32 v193, v77, s0
	v_cvt_pk_bf16_f32 v194, v78, s0
	v_cvt_pk_bf16_f32 v195, v79, s0
	v_cvt_pk_bf16_f32 v196, v80, s0
	v_cvt_pk_bf16_f32 v197, v81, s0
	v_cvt_pk_bf16_f32 v198, v82, s0
	v_cvt_pk_bf16_f32 v199, v83, s0
	s_and_b64 s[2:3], s[0:1], exec
	s_cselect_b32 s2, s4, s7
	s_waitcnt lgkmcnt(11)
	v_mfma_f32_16x16x32_bf16 v[92:95], v[96:99], v[208:211], v[92:95]
	ds_read2_b32 v[246:247], v184 offset1:1
	v_perm_b32 v190, v197, v196, s25
	v_perm_b32 v189, v195, v194, s25
	v_perm_b32 v188, v193, v192, s25
	v_perm_b32 v191, v199, v198, s25
	s_add_i32 s4, s2, s22
	s_and_b64 s[2:3], s[0:1], exec
	s_cselect_b32 s2, s5, s6
	s_add_i32 s2, s2, s21
	s_cmp_lt_u32 s24, 5
	s_waitcnt lgkmcnt(11)
	v_mfma_f32_16x16x32_bf16 v[92:95], v[188:191], v[212:215], v[92:95]
	ds_read_b64_tr_b16 v[248:249], v146 offset:27968
	s_cselect_b32 s2, s4, s2
	s_ashr_i32 s3, s2, 31
	s_lshl_b64 s[36:37], s[2:3], 10
	s_nop 3
	v_cvt_pk_bf16_f32 v92, v92, v93
	v_cvt_pk_bf16_f32 v93, v94, v95
	v_lshl_add_u64 v[94:95], v[100:101], 0, s[36:37]
	global_store_dwordx2 v[94:95], v[92:93], off
	s_waitcnt lgkmcnt(10)
	v_mfma_f32_16x16x32_bf16 v[92:95], v[200:203], v[224:227], 0
	ds_read_b64_tr_b16 v[250:251], v147 offset:27968
	ds_read2_b32 v[204:205], v164 offset1:1
	v_mfma_f32_16x16x32_bf16 v[92:95], v[96:99], v[216:219], v[92:95]
	s_waitcnt lgkmcnt(11)
	v_mfma_f32_16x16x32_bf16 v[92:95], v[188:191], v[228:231], v[92:95]
	ds_read2_b32 v[206:207], v165 offset1:1
	s_nop 7
	v_cvt_pk_bf16_f32 v92, v92, v93
	v_cvt_pk_bf16_f32 v93, v94, v95
	v_lshl_add_u64 v[94:95], v[102:103], 0, s[36:37]
	global_store_dwordx2 v[94:95], v[92:93], off
	s_waitcnt lgkmcnt(11)
	v_pk_mul_f32 v[88:89], v[88:89], v[232:233]
	ds_read_b64_tr_b16 v[208:209], v146 offset:28000
	s_waitcnt lgkmcnt(11)
	v_pk_mul_f32 v[90:91], v[90:91], v[234:235]
	ds_read_b64_tr_b16 v[210:211], v147 offset:28000
	s_waitcnt lgkmcnt(9)
	v_mfma_f32_16x16x32_bf16 v[88:91], v[236:239], v[200:203], v[88:91]
	ds_read2_b32 v[212:213], v187 offset1:1
	ds_read2_b32 v[214:215], v186 offset1:1
	s_waitcnt lgkmcnt(9)
	v_pk_mul_f32 v[72:73], v[72:73], v[244:245]
	s_waitcnt lgkmcnt(8)
	v_pk_mul_f32 v[74:75], v[74:75], v[246:247]
	s_nop 1
	v_mfma_f32_16x16x32_bf16 v[72:75], v[240:243], v[200:203], v[72:75]
	s_waitcnt lgkmcnt(5)
	v_pk_mul_f32 v[76:77], v[76:77], v[204:205]
	s_waitcnt lgkmcnt(4)
	v_pk_mul_f32 v[78:79], v[78:79], v[206:207]
	s_nop 1
	v_mfma_f32_16x16x32_bf16 v[76:79], v[248:251], v[200:203], v[76:79]
	s_waitcnt vmcnt(11)
	ds_write_b128 v121, v[48:51] offset:11776
	s_waitcnt vmcnt(10)
	ds_write_b128 v122, v[56:59]
	s_waitcnt lgkmcnt(3)
	v_pk_mul_f32 v[80:81], v[80:81], v[212:213]
	s_waitcnt lgkmcnt(2)
	v_pk_mul_f32 v[82:83], v[82:83], v[214:215]
	s_nop 1
	v_mfma_f32_16x16x32_bf16 v[84:87], v[208:211], v[200:203], v[80:83]
	s_and_saveexec_b64 s[36:37], s[38:39]
	ds_write_b128 v148, v[52:55]
	s_or_b64 exec, exec, s[36:37]
	s_and_saveexec_b64 s[36:37], s[40:41]
	ds_write_b32 v149, v119 offset:19968
	s_or_b64 exec, exec, s[36:37]
	s_cmp_gt_u32 s24, 61
	s_waitcnt lgkmcnt(0)
	s_barrier
	s_cbranch_scc1 .LBB0_630
	v_add_u32_e32 v48, 0x100, v150
	s_movk_i32 s2, 0x100
	v_cmp_gt_i32_e32 vcc, s2, v48
	v_mov_b32_e32 v50, s21
	v_mov_b32_e32 v51, s22
	v_cndmask_b32_e32 v49, v174, v175, vcc
	v_add3_u32 v49, v132, v49, s27
	v_cndmask_b32_e32 v48, v150, v48, vcc
	v_add_u32_e32 v49, 0xfffff661, v49
	v_cndmask_b32_e32 v50, v50, v51, vcc
	v_cndmask_b32_e64 v48, v49, v48, s[0:1]
	v_add_u32_e32 v48, v48, v50
	s_movk_i32 s2, 0x3800
	v_add_co_u32_e32 v56, vcc, 0xa000, v112
	v_mad_i64_i32 v[48:49], s[2:3], v48, s2, v[104:105]
	s_nop 0
	v_addc_co_u32_e32 v57, vcc, 0, v113, vcc
	global_load_dwordx4 v[48:51], v[48:49], off offset:1024
	s_nop 0
	global_load_dwordx4 v[56:59], v[56:57], off nt
	s_and_saveexec_b64 s[36:37], s[38:39]
	s_cbranch_execz .LBB0_627
	v_lshl_add_u64 v[52:53], v[106:107], 0, s[44:45]
	v_add_co_u32_e32 v52, vcc, 0x12841000, v52
	s_nop 1
	v_addc_co_u32_e32 v53, vcc, 0, v53, vcc
	global_load_dwordx4 v[52:55], v[52:53], off nt

; DI void gla_scan_item(const P& p, int seq, unsigned char* smem) {
;     ...
;     auto loadr = [&](GlaRegs& R, int c) {
;         if (c >= 72) return;
;         { const int pos = tid >> 4, ch = tid & 15; R.rv = *(const u32x4*)(S + (size_t)prow(b, dir, 32 * c + pos) * NP + C_GLA_V + 128 * h + 8 * ch); }
;         { const int t2 = tid & 255, pos = t2 >> 3, ch = t2 & 7; const bf16_t* src = (tid < 256 ? QT : KO) + ((size_t)seq * PT + 32 * c + pos) * 64 + 8 * ch; R.rq = __builtin_nontemporal_load((const u32x4*)src); }
;         if (tid < 128) { const int i = tid >> 2, ch = tid & 3; R.ra = __builtin_nontemporal_load((const u32x4*)(AT + (((size_t)seq * 72 + c) * 32 + i) * 32 + 8 * ch)); }
;     ...
;     auto compute = [&](int c) {
;         const unsigned char* base = smem + (c & 1) * BUFB;
;         const bf16_t* sat = (const bf16_t*)base; const bf16_t* sqt = (const bf16_t*)(base + 2560); const bf16_t* sko = (const bf16_t*)(base + 2560 + 4608); const bf16_t* sv = (const bf16_t*)(base + 2560 + 9216); const float* sdc = (const float*)(base + 2560 + 9216 + 8704);
;         const int dv0 = 16 * w;
;         const bf16x8 vb = tr2(sv + (8 * g + q4) * 136 + dv0 + 4 * p4, sv + (8 * g + 4 + q4) * 136 + dv0 + 4 * p4);
;         bf16x8 bs[2];
;         bs[0] = packacc(st[0], st[1]); bs[1] = packacc(st[2], st[3]);
; #pragma unroll
;         for (int mt = 0; mt < 2; ++mt) {
;             f32x4 acc = (f32x4){0.f, 0.f, 0.f, 0.f};
;             acc = mfma16(vb, ld8(sat + (16 * mt + l15) * 40 + 8 * g), acc);
; #pragma unroll
;             for (int ks = 0; ks < 2; ++ks) {
;                 const bf16_t* r0 = sqt + (16 * mt + l15) * 72 + 32 * ks + 4 * g;
;                 acc = mfma16(bs[ks], ld4x2(r0, r0 + 16), acc);
;             }
;             bf16_t* ob = OG + (size_t)prow(b, dir, 32 * c) * 512 + 128 * h;
;             u32x2 ov; ov.x = pk2(acc[0], acc[1]); ov.y = pk2(acc[2], acc[3]);
;             *(u32x2*)(ob + sgn * ((16 * mt + l15) * 512) + dv0 + 4 * g) = ov;
;         }
; #pragma unroll
;         for (int dt = 0; dt < 4; ++dt) {
;             const bf16x8 ak = tr2(sko + (8 * g + q4) * 72 + 16 * dt + 4 * p4, sko + (8 * g + 4 + q4) * 72 + 16 * dt + 4 * p4);
; #pragma unroll
;             for (int r = 0; r < 4; ++r) st[dt][r] *= sdc[16 * dt + 4 * g + r];
;             st[dt] = mfma16(ak, vb, st[dt]);
;         }
;     };
.LBB0_630:
	ds_read_b64_tr_b16 v[200:201], v123 offset:11776
	ds_read_b64_tr_b16 v[202:203], v124 offset:11776
	ds_read_b128 v[204:207], v125
	ds_read2_b64 v[208:211], v152 offset0:64 offset1:68
	ds_read2_b64 v[212:215], v152 offset0:72 offset1:76
	ds_read2_b64 v[216:219], v151 offset0:64 offset1:68
	ds_read_b128 v[224:227], v127
	ds_read2_b64 v[228:231], v151 offset0:72 offset1:76
	ds_read2_b32 v[232:233], v153 offset1:1
	ds_read2_b32 v[234:235], v156 offset1:1
	ds_read_b64_tr_b16 v[238:239], v144 offset:7168
	ds_read_b64_tr_b16 v[242:243], v144 offset:7200
	v_cvt_pk_bf16_f32 v92, v88, s0
	v_cvt_pk_bf16_f32 v95, v89, s0
	v_cvt_pk_bf16_f32 v93, v90, s0
	v_cvt_pk_bf16_f32 v134, v91, s0
	v_cvt_pk_bf16_f32 v94, v72, s0
	v_cvt_pk_bf16_f32 v135, v73, s0
	v_cvt_pk_bf16_f32 v188, v74, s0
	v_cvt_pk_bf16_f32 v189, v75, s0
	v_perm_b32 v94, v135, v94, s25
	v_perm_b32 v93, v134, v93, s25
	v_perm_b32 v92, v95, v92, s25
	v_perm_b32 v95, v189, v188, s25
	s_waitcnt lgkmcnt(9)
	v_mfma_f32_16x16x32_bf16 v[80:83], v[200:203], v[204:207], 0
	ds_read_b64_tr_b16 v[236:237], v143 offset:7168
	ds_read_b64_tr_b16 v[240:241], v143 offset:7200
	ds_read2_b32 v[244:245], v158 offset1:1
	s_add_i32 s4, s26, 64
	s_add_i32 s5, s26, 0xffffff40
	s_add_i32 s6, s27, 32
	s_add_i32 s7, s27, 0xfffff820
	v_cvt_pk_bf16_f32 v192, v76, s0
	v_cvt_pk_bf16_f32 v193, v77, s0
	v_cvt_pk_bf16_f32 v194, v78, s0
	v_cvt_pk_bf16_f32 v195, v79, s0
	v_cvt_pk_bf16_f32 v196, v84, s0
	v_cvt_pk_bf16_f32 v197, v85, s0
	v_cvt_pk_bf16_f32 v198, v86, s0
	v_cvt_pk_bf16_f32 v199, v87, s0
	s_and_b64 s[2:3], s[0:1], exec
	s_cselect_b32 s2, s4, s7
	s_waitcnt lgkmcnt(11)
	v_mfma_f32_16x16x32_bf16 v[80:83], v[92:95], v[208:211], v[80:83]
	ds_read2_b32 v[246:247], v157 offset1:1
	v_perm_b32 v190, v197, v196, s25
	v_perm_b32 v189, v195, v194, s25
	v_perm_b32 v188, v193, v192, s25
	v_perm_b32 v191, v199, v198, s25
	s_add_i32 s4, s2, s22
	s_and_b64 s[2:3], s[0:1], exec
	s_cselect_b32 s2, s5, s6
	s_add_i32 s2, s2, s21
	s_cmp_lt_u32 s24, 4
	s_waitcnt lgkmcnt(11)
	v_mfma_f32_16x16x32_bf16 v[80:83], v[188:191], v[212:215], v[80:83]
	ds_read_b64_tr_b16 v[248:249], v143 offset:7232
	s_cselect_b32 s2, s4, s2
	s_ashr_i32 s3, s2, 31
	s_lshl_b64 s[36:37], s[2:3], 10
	s_nop 3
	v_cvt_pk_bf16_f32 v80, v80, v81
	v_cvt_pk_bf16_f32 v81, v82, v83
	v_lshl_add_u64 v[82:83], v[100:101], 0, s[36:37]
	global_store_dwordx2 v[82:83], v[80:81], off
	s_waitcnt lgkmcnt(10)
	v_mfma_f32_16x16x32_bf16 v[80:83], v[200:203], v[224:227], 0
	ds_read_b64_tr_b16 v[250:251], v144 offset:7232
	ds_read2_b32 v[204:205], v154 offset1:1
	v_mfma_f32_16x16x32_bf16 v[80:83], v[92:95], v[216:219], v[80:83]
	s_waitcnt lgkmcnt(11)
	v_mfma_f32_16x16x32_bf16 v[80:83], v[188:191], v[228:231], v[80:83]
	ds_read2_b32 v[206:207], v155 offset1:1
	s_nop 7
	v_cvt_pk_bf16_f32 v80, v80, v81
	v_cvt_pk_bf16_f32 v81, v82, v83
	v_lshl_add_u64 v[82:83], v[102:103], 0, s[36:37]
	global_store_dwordx2 v[82:83], v[80:81], off
	s_waitcnt lgkmcnt(11)
	v_pk_mul_f32 v[80:81], v[88:89], v[232:233]
	ds_read_b64_tr_b16 v[208:209], v143 offset:7264
	s_waitcnt lgkmcnt(11)
	v_pk_mul_f32 v[82:83], v[90:91], v[234:235]
	ds_read_b64_tr_b16 v[210:211], v144 offset:7264
	s_waitcnt lgkmcnt(9)
	v_mfma_f32_16x16x32_bf16 v[92:95], v[236:239], v[200:203], v[80:83]
	ds_read2_b32 v[212:213], v161 offset1:1
	ds_read2_b32 v[214:215], v160 offset1:1
	s_nop 2
	s_waitcnt lgkmcnt(9)
	v_pk_mul_f32 v[72:73], v[72:73], v[244:245]
	s_waitcnt lgkmcnt(8)
	v_pk_mul_f32 v[74:75], v[74:75], v[246:247]
	s_nop 1
	v_mfma_f32_16x16x32_bf16 v[72:75], v[240:243], v[200:203], v[72:75]
	s_waitcnt lgkmcnt(5)
	v_pk_mul_f32 v[76:77], v[76:77], v[204:205]
	s_waitcnt lgkmcnt(4)
	v_pk_mul_f32 v[78:79], v[78:79], v[206:207]
	s_nop 1
	v_mfma_f32_16x16x32_bf16 v[80:83], v[248:251], v[200:203], v[76:79]
	s_nop 2
	s_waitcnt vmcnt(11)
	ds_write_b128 v121, v[60:63] offset:32512
	s_waitcnt vmcnt(10)
	ds_write_b128 v122, v[68:71] offset:20736
	s_waitcnt lgkmcnt(3)
	v_pk_mul_f32 v[84:85], v[84:85], v[212:213]
	s_waitcnt lgkmcnt(2)
	v_pk_mul_f32 v[86:87], v[86:87], v[214:215]
	s_nop 1
	v_mfma_f32_16x16x32_bf16 v[88:91], v[208:211], v[200:203], v[84:87]
	s_and_saveexec_b64 s[36:37], s[38:39]
	ds_write_b128 v148, v[64:67] offset:20736
	s_or_b64 exec, exec, s[36:37]
	s_and_saveexec_b64 s[36:37], s[40:41]
	ds_write_b32 v149, v120 offset:40704
	s_or_b64 exec, exec, s[36:37]
	s_cmp_gt_u32 s24, 60
	s_waitcnt lgkmcnt(0)
	s_barrier
	s_cbranch_scc1 .LBB0_579
	v_add_u32_e32 v60, 0x120, v150
	s_movk_i32 s2, 0x100
	v_cmp_gt_i32_e32 vcc, s2, v60
	v_add_u32_e32 v61, 32, v150
	v_mov_b32_e32 v63, s22
	v_cndmask_b32_e32 v62, v174, v175, vcc
	v_add3_u32 v62, v132, v62, s27
	v_cndmask_b32_e32 v60, v61, v60, vcc
	v_mov_b32_e32 v61, s21
	v_add_u32_e32 v62, 0xfffff641, v62
	v_cndmask_b32_e32 v61, v61, v63, vcc
	v_cndmask_b32_e64 v60, v62, v60, s[0:1]
	v_add_u32_e32 v60, v60, v61
	s_movk_i32 s2, 0x3800
	v_add_co_u32_e32 v68, vcc, 0xb000, v112
	v_mad_i64_i32 v[60:61], s[2:3], v60, s2, v[104:105]
	s_nop 0
	v_addc_co_u32_e32 v69, vcc, 0, v113, vcc
	global_load_dwordx4 v[60:63], v[60:61], off offset:1024
	s_nop 0
	global_load_dwordx4 v[68:71], v[68:69], off nt
	s_and_saveexec_b64 s[36:37], s[38:39]
	s_cbranch_execz .LBB0_637
	v_lshl_add_u64 v[64:65], v[106:107], 0, s[44:45]
	v_add_co_u32_e32 v64, vcc, 0x12841000, v64
	s_nop 1
	v_addc_co_u32_e32 v65, vcc, 0, v65, vcc
	global_load_dwordx4 v[64:67], v[64:65], off offset:2048 nt
